# XCD-local barriers: L1 invalidate issued at barrier entry (overlapping the arrival atomic) instead of after completion; P8 gain loads merged
# speedup vs baseline: 1.0156x; 1.0156x over previous
.LBB0_498:
	s_waitcnt vmcnt(0)
	s_barrier
	s_and_saveexec_b64 s[4:5], s[10:11]
	s_cbranch_execz .LBB0_550
	s_add_i32 s6, 0, 0x20160
	v_mov_b32_e32 v0, s6
	s_waitcnt vmcnt(0) expcnt(0) lgkmcnt(0)
	s_cmp_eq_u32 s98, 0
	s_cbranch_scc1 .Leinv_1
	buffer_inv sc1
.Leinv_1:
	ds_read_b32 v2, v0
	s_add_i32 s6, 0, 0x20164
	v_mov_b32_e32 v0, s6
	ds_read_b32 v0, v0
	s_waitcnt lgkmcnt(1)
	v_cmp_ne_u32_e32 vcc, 0, v2
	s_cbranch_vccnz .LBB0_514
	s_load_dwordx2 s[12:13], s[0:1], 0xa8
	s_load_dword s9, s[0:1], 0xb0
	s_add_u32 s6, s34, 0x4200
	s_addc_u32 s7, s35, 0
	s_add_u32 s8, s34, 0x4400
	s_waitcnt lgkmcnt(0)
	s_mul_i32 s54, s13, s12
	s_mul_i32 s54, s54, s9
	s_addc_u32 s9, s35, 0
	s_add_u32 s12, s34, 0x4500
	s_addc_u32 s13, s35, 0
	s_add_u32 s14, s34, 0x4600
	s_addc_u32 s15, s35, 0
	s_add_u32 s16, s34, 0x4700
	s_addc_u32 s17, s35, 0
	s_add_u32 s18, s34, 0x4800
	s_addc_u32 s19, s35, 0
	s_add_u32 s20, s34, 0x4900
	s_addc_u32 s21, s35, 0
	s_add_u32 s22, s34, 0x4a00
	s_addc_u32 s23, s35, 0
	s_add_u32 s24, s34, 0x4b00
	s_addc_u32 s25, s35, 0
	s_add_u32 s26, s34, 0x4c00
	s_addc_u32 s27, s35, 0
	s_add_u32 s28, s34, 0x4d00
	s_addc_u32 s29, s35, 0
	s_add_u32 s30, s34, 0x4e00
	s_addc_u32 s31, s35, 0
	s_add_u32 s36, s34, 0x4f00
	s_addc_u32 s37, s35, 0
	s_add_u32 s38, s34, 0x5000
	s_addc_u32 s39, s35, 0
	s_add_u32 s40, s34, 0x5100
	s_addc_u32 s41, s35, 0
	s_add_u32 s42, s34, 0x5200
	s_addc_u32 s43, s35, 0
	s_add_u32 s44, s34, 0x5300
	s_addc_u32 s45, s35, 0
	s_mov_b32 s55, 1
	v_mov_b32_e32 v16, 0
	s_branch .LBB0_502

.LBB0_529:
	s_or_b64 exec, exec, s[12:13]
	s_waitcnt vmcnt(0)
	s_cmp_lg_u32 s98, 0
	s_cbranch_scc1 .Llinv_1_0
	buffer_inv sc1
.Llinv_1_0:
	s_waitcnt vmcnt(0)
.LBB0_530:
	s_andn2_saveexec_b64 s[8:9], s[8:9]
	s_cbranch_execz .LBB0_550
	s_mov_b64 s[8:9], exec
	s_waitcnt lgkmcnt(0)
	s_cmp_lg_u32 s98, 0
	s_cbranch_scc1 .Lfastbar_1
	buffer_wbl2 sc1
	s_waitcnt lgkmcnt(0)
	s_waitcnt vmcnt(0)
	v_mbcnt_lo_u32_b32 v1, s8, 0
	v_mbcnt_hi_u32_b32 v1, s9, v1
	v_cmp_eq_u32_e32 vcc, 0, v1
	s_and_saveexec_b64 s[12:13], vcc
	s_cbranch_execz .LBB0_533
	s_bcnt1_i32_b64 s8, s[8:9]
	v_mov_b32_e32 v2, 0x7000
	v_mov_b32_e32 v3, s8
	global_atomic_add v2, v2, v3, s[34:35] offset:1024 sc0

.Lfastbar_1:
	s_mov_b64 s[8:9], exec
	v_mbcnt_lo_u32_b32 v0, s8, 0
	v_mbcnt_hi_u32_b32 v0, s9, v0
	v_cmp_eq_u32_e32 vcc, 0, v0
	s_waitcnt vmcnt(0)
	s_cmp_lg_u32 s98, 0
	s_cbranch_scc1 .Llinv_1_1
	buffer_inv sc1
.Llinv_1_1:
	s_and_saveexec_b64 s[12:13], vcc
	s_cbranch_execz .LBB0_549
	s_bcnt1_i32_b64 s8, s[8:9]
	v_mov_b32_e32 v0, 0x2000
	v_mov_b32_e32 v1, s8
	global_atomic_add v0, v1, s[6:7] offset:1024

.LBB0_558:
	s_barrier
	s_waitcnt vmcnt(0)
	s_barrier
	s_and_saveexec_b64 s[4:5], s[10:11]
	s_cbranch_execz .LBB0_610
	s_add_i32 s6, 0, 0x20160
	s_waitcnt vmcnt(12)
	v_mov_b32_e32 v0, s6
	s_waitcnt vmcnt(0) expcnt(0) lgkmcnt(0)
	s_cmp_eq_u32 s98, 0
	s_cbranch_scc1 .Leinv_2
	buffer_inv sc1

.Llinv_2_0:
	s_waitcnt vmcnt(0)
.LBB0_590:
	s_andn2_saveexec_b64 s[8:9], s[8:9]
	s_cbranch_execz .LBB0_610
	s_mov_b64 s[8:9], exec
	s_waitcnt lgkmcnt(0)
	s_cmp_lg_u32 s98, 0
	s_cbranch_scc1 .Lfastbar_2
	buffer_wbl2 sc1
	s_waitcnt lgkmcnt(0)
	s_waitcnt vmcnt(0)
	v_mbcnt_lo_u32_b32 v1, s8, 0
	v_mbcnt_hi_u32_b32 v1, s9, v1
	v_cmp_eq_u32_e32 vcc, 0, v1
	s_and_saveexec_b64 s[12:13], vcc
	s_cbranch_execz .LBB0_593
	s_bcnt1_i32_b64 s8, s[8:9]
	v_mov_b32_e32 v2, 0x7000
	v_mov_b32_e32 v3, s8
	global_atomic_add v2, v2, v3, s[34:35] offset:1024 sc0

.LBB0_621:
	s_waitcnt vmcnt(0)
	s_barrier
	s_and_saveexec_b64 s[4:5], s[10:11]
	s_cbranch_execz .LBB0_673
	s_add_i32 s6, 0, 0x20160
	s_waitcnt vmcnt(23)
	v_mov_b32_e32 v0, s6
	s_waitcnt vmcnt(0) expcnt(0) lgkmcnt(0)
	s_cmp_eq_u32 s98, 0
	s_cbranch_scc1 .Leinv_3
	buffer_inv sc1

.Llinv_3_0:
	s_waitcnt vmcnt(0)
.LBB0_653:
	s_andn2_saveexec_b64 s[8:9], s[8:9]
	s_cbranch_execz .LBB0_673
	s_mov_b64 s[8:9], exec
	s_waitcnt lgkmcnt(0)
	s_cmp_lg_u32 s98, 0
	s_cbranch_scc1 .Lfastbar_3
	buffer_wbl2 sc1
	s_waitcnt lgkmcnt(0)
	s_waitcnt vmcnt(0)
	v_mbcnt_lo_u32_b32 v1, s8, 0
	v_mbcnt_hi_u32_b32 v1, s9, v1
	v_cmp_eq_u32_e32 vcc, 0, v1
	s_and_saveexec_b64 s[12:13], vcc
	s_cbranch_execz .LBB0_656
	s_bcnt1_i32_b64 s8, s[8:9]
	v_mov_b32_e32 v2, 0x7000
	v_mov_b32_e32 v3, s8
	global_atomic_add v2, v2, v3, s[34:35] offset:1024 sc0

.LBB0_723:
	s_waitcnt vmcnt(0)
	s_waitcnt lgkmcnt(0)
	s_barrier
	s_and_saveexec_b64 s[4:5], s[10:11]
	s_cbranch_execz .LBB0_775
	s_add_i32 s6, 0, 0x20160
	v_mov_b32_e32 v0, s6
	s_waitcnt vmcnt(0) expcnt(0) lgkmcnt(0)
	s_cmp_eq_u32 s98, 0
	s_cbranch_scc1 .Leinv_4
	buffer_inv sc1

.Llinv_4_0:
	s_waitcnt vmcnt(0)
.LBB0_755:
	s_andn2_saveexec_b64 s[8:9], s[8:9]
	s_cbranch_execz .LBB0_775
	s_mov_b64 s[8:9], exec
	s_waitcnt lgkmcnt(0)
	s_cmp_lg_u32 s98, 0
	s_cbranch_scc1 .Lfastbar_4
	buffer_wbl2 sc1
	s_waitcnt lgkmcnt(0)
	s_waitcnt vmcnt(0)
	v_mbcnt_lo_u32_b32 v1, s8, 0
	v_mbcnt_hi_u32_b32 v1, s9, v1
	v_cmp_eq_u32_e32 vcc, 0, v1
	s_and_saveexec_b64 s[12:13], vcc
	s_cbranch_execz .LBB0_758
	s_bcnt1_i32_b64 s8, s[8:9]
	v_mov_b32_e32 v2, 0x7000
	v_mov_b32_e32 v3, s8
	global_atomic_add v2, v2, v3, s[34:35] offset:1024 sc0

.Llinv_5_0:
	s_waitcnt vmcnt(0)
.LBB0_823:
	s_andn2_saveexec_b64 s[8:9], s[8:9]
	s_cbranch_execz .LBB0_843
	s_mov_b64 s[8:9], exec
	s_waitcnt lgkmcnt(0)
	s_cmp_lg_u32 s98, 0
	s_cbranch_scc1 .Lfastbar_5
	buffer_wbl2 sc1
	s_waitcnt lgkmcnt(0)
	s_waitcnt vmcnt(0)
	v_mbcnt_lo_u32_b32 v1, s8, 0
	v_mbcnt_hi_u32_b32 v1, s9, v1
	v_cmp_eq_u32_e32 vcc, 0, v1
	s_and_saveexec_b64 s[12:13], vcc
	s_cbranch_execz .LBB0_826
	s_bcnt1_i32_b64 s8, s[8:9]
	v_mov_b32_e32 v2, 0x7000
	v_mov_b32_e32 v3, s8
	global_atomic_add v2, v2, v3, s[34:35] offset:1024 sc0

.Llinv_6_0:
	s_waitcnt vmcnt(0)
.LBB0_921:
	s_andn2_saveexec_b64 s[8:9], s[8:9]
	s_cbranch_execz .LBB0_941
	s_mov_b64 s[8:9], exec
	s_waitcnt lgkmcnt(0)
	s_cmp_lg_u32 s98, 0
	s_cbranch_scc1 .Lfastbar_6
	buffer_wbl2 sc1
	s_waitcnt lgkmcnt(0)
	s_waitcnt vmcnt(0)
	v_mbcnt_lo_u32_b32 v1, s8, 0
	v_mbcnt_hi_u32_b32 v1, s9, v1
	v_cmp_eq_u32_e32 vcc, 0, v1
	s_and_saveexec_b64 s[12:13], vcc
	s_cbranch_execz .LBB0_924
	s_bcnt1_i32_b64 s8, s[8:9]
	v_mov_b32_e32 v2, 0x7000
	v_mov_b32_e32 v3, s8
	global_atomic_add v2, v2, v3, s[34:35] offset:1024 sc0

.LBB0_955:
	s_ashr_i32 s27, s38, 2
	s_cmp_eq_u32 s27, 2
	s_cselect_b64 vcc, -1, 0
	s_cmp_lt_u32 s38, 4
	s_cselect_b64 s[40:41], -1, 0
	v_mbcnt_lo_u32_b32 v166, -1, 0
	v_mbcnt_hi_u32_b32 v166, -1, v166
	s_and_b64 s[6:7], s[40:41], exec
	v_ashrrev_i32_e32 v144, 1, v166
	s_cselect_b32 s6, s13, s9
	s_cselect_b32 s7, s12, s8
	v_and_b32_e32 v144, -8, v144
	v_cndmask_b32_e32 v162, 1.0, v183, vcc
	v_mov_b32_e32 v148, s7
	v_mov_b32_e32 v149, s6
	v_ashrrev_i32_e32 v145, 31, v144
	s_cmp_lg_u32 s27, 1
	v_mov_b32_e32 v146, 1.0
	v_lshl_add_u64 v[164:165], v[144:145], 2, v[148:149]
	s_cselect_b64 s[44:45], -1, 0
	s_cmp_eq_u32 s27, 1
	v_mov_b32_e32 v163, v162
	v_mov_b32_e32 v148, 1.0
	v_mov_b32_e32 v149, 1.0
	v_mov_b32_e32 v150, 1.0
	v_mov_b32_e32 v151, 1.0
	v_mov_b32_e32 v147, 1.0
	v_mov_b32_e32 v152, 1.0
	v_mov_b32_e32 v153, 1.0
	v_mov_b32_e32 v154, 1.0
	v_mov_b32_e32 v155, 1.0
	v_mov_b32_e32 v156, 1.0
	v_mov_b32_e32 v157, 1.0
	v_mov_b32_e32 v158, 1.0
	v_mov_b32_e32 v159, 1.0
	v_mov_b32_e32 v160, 1.0
	v_mov_b32_e32 v161, 1.0
	s_cbranch_scc1 .Lp8g_skip
	global_load_dwordx4 v[148:151], v[164:165], off
	global_load_dwordx4 v[224:227], v[164:165], off offset:16
	global_load_dwordx4 v[228:231], v[164:165], off offset:128
	global_load_dwordx4 v[232:235], v[164:165], off offset:144
	s_waitcnt vmcnt(0)
	v_pk_mul_f32 v[150:151], v[162:163], v[150:151]
	v_pk_mul_f32 v[148:149], v[162:163], v[148:149]
	v_pk_mul_f32 v[152:153], v[162:163], v[226:227]
	v_pk_mul_f32 v[146:147], v[162:163], v[224:225]
	v_pk_mul_f32 v[158:159], v[162:163], v[230:231]
	v_pk_mul_f32 v[156:157], v[162:163], v[228:229]
	v_pk_mul_f32 v[160:161], v[162:163], v[234:235]
	v_pk_mul_f32 v[154:155], v[162:163], v[232:233]
.Lp8g_skip:
.LBB0_957:
.LBB0_959:
.LBB0_961:
.LBB0_963:
	s_lshl_b32 s6, s42, 8
	s_add_i32 s6, s6, s62
	v_and_or_b32 v176, v166, 15, s6
	v_ashrrev_i32_e32 v177, 31, v176
	v_lshl_add_u64 v[162:163], v[176:177], 2, s[18:19]
	v_or_b32_e32 v174, 16, v176
	v_or_b32_e32 v172, 32, v176
	global_load_dword v191, v[162:163], off
	v_ashrrev_i32_e32 v175, 31, v174
	v_ashrrev_i32_e32 v173, 31, v172
	v_or_b32_e32 v170, 48, v176
	v_add_u32_e32 v168, 0x80, v176
	v_add_u32_e32 v166, 0x90, v176
	v_add_u32_e32 v164, 0xa0, v176
	v_add_u32_e32 v162, 0xb0, v176
	v_lshl_add_u64 v[184:185], v[174:175], 2, s[18:19]
	v_lshl_add_u64 v[186:187], v[172:173], 2, s[18:19]
	v_ashrrev_i32_e32 v171, 31, v170
	v_ashrrev_i32_e32 v169, 31, v168
	v_ashrrev_i32_e32 v167, 31, v166
	v_ashrrev_i32_e32 v165, 31, v164
	v_ashrrev_i32_e32 v163, 31, v162
	v_lshl_add_u64 v[192:193], v[170:171], 2, s[18:19]
	v_lshl_add_u64 v[194:195], v[168:169], 2, s[18:19]
	v_lshl_add_u64 v[196:197], v[166:167], 2, s[18:19]
	v_lshl_add_u64 v[198:199], v[164:165], 2, s[18:19]
	v_lshl_add_u64 v[200:201], v[162:163], 2, s[18:19]
	global_load_dword v190, v[184:185], off
	global_load_dword v189, v[186:187], off
	global_load_dword v188, v[192:193], off
	s_nop 0
	global_load_dword v187, v[194:195], off
	global_load_dword v186, v[196:197], off
	global_load_dword v185, v[198:199], off
	global_load_dword v184, v[200:201], off
	s_and_b32 s27, s38, -4
	s_cmp_lg_u32 s27, 4
	s_cselect_b64 s[42:43], -1, 0
	s_lshl_b32 s27, s38, 8
	s_and_b32 s27, s27, 0x300
	s_mov_b64 s[6:7], -1
	s_and_b64 vcc, exec, s[42:43]
	s_or_b32 s29, s27, s66
	s_waitcnt vmcnt(0)
	v_fmamk_f32 v191, v191, 0x3a800000, v182
	v_rsq_f32_e32 v192, v191
	s_nop 0
	v_pk_mul_f32 v[126:127], v[126:127], v[192:193] op_sel_hi:[1,0]
	v_pk_mul_f32 v[124:125], v[124:125], v[192:193] op_sel_hi:[1,0]
	v_pk_mul_f32 v[122:123], v[122:123], v[192:193] op_sel_hi:[1,0]
	v_pk_mul_f32 v[120:121], v[120:121], v[192:193] op_sel_hi:[1,0]
	v_pk_mul_f32 v[118:119], v[118:119], v[192:193] op_sel_hi:[1,0]
	v_pk_mul_f32 v[116:117], v[116:117], v[192:193] op_sel_hi:[1,0]
	v_pk_mul_f32 v[114:115], v[114:115], v[192:193] op_sel_hi:[1,0]
	v_pk_mul_f32 v[112:113], v[112:113], v[192:193] op_sel_hi:[1,0]
	s_cbranch_vccz .LBB0_965
	v_pk_mul_f32 v[192:193], v[126:127], v[126:127]
	v_pk_mul_f32 v[194:195], v[124:125], v[124:125]
	s_and_b64 s[6:7], s[40:41], exec
	v_pk_mov_b32 v[196:197], v[194:195], v[192:193] op_sel:[1,0]
	v_mov_b32_e32 v195, v193
	v_pk_add_f32 v[192:193], v[196:197], v[194:195]
	v_pk_mul_f32 v[194:195], v[122:123], v[122:123]
	v_pk_add_f32 v[192:193], v[192:193], v[192:193] op_sel_hi:[0,1]
	v_pk_mul_f32 v[196:197], v[120:121], v[120:121]
	v_mul_f32_e32 v192, v116, v116
	v_pk_mov_b32 v[198:199], v[196:197], v[194:195] op_sel:[1,0]
	v_mov_b32_e32 v197, v195
	v_pk_add_f32 v[194:195], v[198:199], v[196:197]
	v_pk_fma_f32 v[196:197], v[116:117], v[116:117], v[192:193] op_sel_hi:[1,1,0]
	v_mul_f32_e32 v192, v118, v118
	v_pk_add_f32 v[194:195], v[194:195], v[194:195] op_sel_hi:[0,1]
	v_pk_fma_f32 v[198:199], v[118:119], v[118:119], v[192:193] op_sel_hi:[1,1,0]
	v_mul_f32_e32 v196, v112, v112
	v_mul_f32_e32 v198, v113, v113
	v_mul_f32_e32 v192, v114, v114
	v_mul_f32_e32 v194, v115, v115
	v_pk_add_f32 v[196:197], v[196:197], v[198:199]
	v_pk_add_f32 v[192:193], v[192:193], v[194:195]
	s_cselect_b32 s7, s59, s61
	v_pk_add_f32 v[192:193], v[196:197], v[192:193]
	s_cselect_b32 s6, s58, s60
	v_add_f32_e32 v191, v192, v193
	ds_swizzle_b32 v192, v191 offset:swizzle(SWAP,16)
	v_pk_mul_f32 v[194:195], v[148:149], v[124:125]
	v_pk_mul_f32 v[202:203], v[146:147], v[120:121]
	s_waitcnt lgkmcnt(0)
	v_add_f32_e32 v191, v191, v192
	v_mov_b32_e32 v192, v191
	s_nop 1
	v_permlane32_swap_b32_e32 v191, v192
	v_add_f32_e32 v191, v191, v192
	v_fmamk_f32 v191, v191, 0x3c800000, v182
	v_rsq_f32_e32 v196, v191
	v_lshlrev_b64 v[192:193], 11, v[176:177]
	v_lshl_add_u64 v[192:193], s[6:7], 0, v[192:193]
	s_lshl_b32 s6, s29, 1
	s_mov_b32 s7, s15
	v_lshl_add_u64 v[192:193], v[192:193], 0, s[6:7]
	v_lshl_add_u64 v[198:199], v[144:145], 1, v[192:193]
	v_pk_mul_f32 v[192:193], v[150:151], v[126:127]
	s_mov_b64 s[6:7], 0
	v_pk_mul_f32 v[200:201], v[192:193], v[196:197] op_sel_hi:[1,0]
	v_pk_mul_f32 v[192:193], v[194:195], v[196:197] op_sel_hi:[1,0]
	v_pk_mul_f32 v[194:195], v[152:153], v[122:123]
	v_cvt_pk_bf16_f32 v192, v192, v193
	v_pk_mul_f32 v[204:205], v[194:195], v[196:197] op_sel_hi:[1,0]
	v_pk_mul_f32 v[194:195], v[202:203], v[196:197] op_sel_hi:[1,0]
	v_cvt_pk_bf16_f32 v193, v200, v201
	v_cvt_pk_bf16_f32 v194, v194, v195
	v_cvt_pk_bf16_f32 v195, v204, v205
	global_store_dwordx4 v[198:199], v[192:195], off
	v_pk_mul_f32 v[202:203], v[154:155], v[112:113]
	s_nop 0
	v_pk_mul_f32 v[192:193], v[158:159], v[118:119]
	v_pk_mul_f32 v[194:195], v[156:157], v[116:117]
	v_pk_mul_f32 v[200:201], v[192:193], v[196:197] op_sel_hi:[1,0]
	v_pk_mul_f32 v[192:193], v[194:195], v[196:197] op_sel_hi:[1,0]
	v_pk_mul_f32 v[194:195], v[160:161], v[114:115]
	v_cvt_pk_bf16_f32 v192, v192, v193
	v_pk_mul_f32 v[204:205], v[194:195], v[196:197] op_sel_hi:[1,0]
	v_pk_mul_f32 v[194:195], v[202:203], v[196:197] op_sel_hi:[1,0]
	v_cvt_pk_bf16_f32 v193, v200, v201
	v_cvt_pk_bf16_f32 v194, v194, v195
	v_cvt_pk_bf16_f32 v195, v204, v205
	global_store_dwordx4 v[198:199], v[192:195], off offset:64

.Llinv_7_0:
	s_waitcnt vmcnt(0)
.LBB0_1031:
	s_andn2_saveexec_b64 s[8:9], s[8:9]
	s_cbranch_execz .LBB0_1051
	s_mov_b64 s[8:9], exec
	s_waitcnt lgkmcnt(0)
	s_cmp_lg_u32 s98, 0
	s_cbranch_scc1 .Lfastbar_7
	buffer_wbl2 sc1
	s_waitcnt lgkmcnt(0)
	s_waitcnt vmcnt(0)
	v_mbcnt_lo_u32_b32 v1, s8, 0
	v_mbcnt_hi_u32_b32 v1, s9, v1
	v_cmp_eq_u32_e32 vcc, 0, v1
	s_and_saveexec_b64 s[12:13], vcc
	s_cbranch_execz .LBB0_1034
	s_bcnt1_i32_b64 s8, s[8:9]
	v_mov_b32_e32 v2, 0x7000
	v_mov_b32_e32 v3, s8
	global_atomic_add v2, v2, v3, s[34:35] offset:1024 sc0

.Llinv_8_0:
	s_waitcnt vmcnt(0)
.LBB0_1107:
	s_andn2_saveexec_b64 s[8:9], s[8:9]
	s_cbranch_execz .LBB0_1127
	s_mov_b64 s[8:9], exec
	s_waitcnt lgkmcnt(0)
	s_cmp_lg_u32 s98, 0
	s_cbranch_scc1 .Lfastbar_8
	buffer_wbl2 sc1
	s_waitcnt lgkmcnt(0)
	s_waitcnt vmcnt(0)
	v_mbcnt_lo_u32_b32 v1, s8, 0
	v_mbcnt_hi_u32_b32 v1, s9, v1
	v_cmp_eq_u32_e32 vcc, 0, v1
	s_and_saveexec_b64 s[12:13], vcc
	s_cbranch_execz .LBB0_1110
	s_bcnt1_i32_b64 s8, s[8:9]
	v_mov_b32_e32 v2, 0x7000
	v_mov_b32_e32 v3, s8
	global_atomic_add v2, v2, v3, s[34:35] offset:1024 sc0

.Llinv_9_0:
	s_waitcnt vmcnt(0)
.LBB0_1201:
	s_andn2_saveexec_b64 s[8:9], s[8:9]
	s_cbranch_execz .LBB0_1221
	s_mov_b64 s[8:9], exec
	s_waitcnt lgkmcnt(0)
	s_cmp_lg_u32 s98, 0
	s_cbranch_scc1 .Lfastbar_9
	buffer_wbl2 sc1
	s_waitcnt lgkmcnt(0)
	s_waitcnt vmcnt(0)
	v_mbcnt_lo_u32_b32 v1, s8, 0
	v_mbcnt_hi_u32_b32 v1, s9, v1
	v_cmp_eq_u32_e32 vcc, 0, v1
	s_and_saveexec_b64 s[12:13], vcc
	s_cbranch_execz .LBB0_1204
	s_bcnt1_i32_b64 s8, s[8:9]
	v_mov_b32_e32 v2, 0x7000
	v_mov_b32_e32 v3, s8
	global_atomic_add v2, v2, v3, s[34:35] offset:1024 sc0

.Leinv_10:
	ds_read_b32 v2, v0
	s_add_i32 s6, 0, 0x20164
	v_mov_b32_e32 v0, s6
	ds_read_b32 v0, v0
	s_waitcnt lgkmcnt(1)
	v_cmp_ne_u32_e32 vcc, 0, v2
	s_cbranch_vccnz .LBB0_1253
	s_load_dwordx2 s[10:11], s[0:1], 0xa8
	s_load_dword s9, s[0:1], 0xb0
	s_add_u32 s6, s34, 0x4200
	s_addc_u32 s7, s35, 0
	s_add_u32 s8, s34, 0x4400
	s_waitcnt lgkmcnt(0)
	s_mul_i32 s50, s11, s10
	s_mul_i32 s50, s50, s9
	s_addc_u32 s9, s35, 0
	s_add_u32 s10, s34, 0x4500
	s_addc_u32 s11, s35, 0
	s_add_u32 s12, s34, 0x4600
	s_addc_u32 s13, s35, 0
	s_add_u32 s14, s34, 0x4700
	s_addc_u32 s15, s35, 0
	s_add_u32 s16, s34, 0x4800
	s_addc_u32 s17, s35, 0
	s_add_u32 s18, s34, 0x4900
	s_addc_u32 s19, s35, 0
	s_add_u32 s20, s34, 0x4a00
	s_addc_u32 s21, s35, 0
	s_add_u32 s22, s34, 0x4b00
	s_addc_u32 s23, s35, 0
	s_add_u32 s24, s34, 0x4c00
	s_addc_u32 s25, s35, 0
	s_add_u32 s26, s34, 0x4d00
	s_addc_u32 s27, s35, 0
	s_add_u32 s28, s34, 0x4e00
	s_addc_u32 s29, s35, 0
	s_add_u32 s30, s34, 0x4f00
	s_addc_u32 s31, s35, 0
	s_add_u32 s36, s34, 0x5000
	s_addc_u32 s37, s35, 0
	s_add_u32 s38, s34, 0x5100
	s_addc_u32 s39, s35, 0
	s_add_u32 s40, s34, 0x5200
	s_addc_u32 s41, s35, 0
	s_add_u32 s42, s34, 0x5300
	s_addc_u32 s43, s35, 0
	s_mov_b32 s51, 1
	v_mov_b32_e32 v16, 0
	s_branch .LBB0_1241

.LBB0_1268:
	s_or_b64 exec, exec, s[10:11]
	s_waitcnt vmcnt(0)
	s_cmp_lg_u32 s98, 0
	s_cbranch_scc1 .Llinv_10_0
	buffer_inv sc1
.Llinv_10_0:
	s_waitcnt vmcnt(0)
.LBB0_1269:
	s_andn2_saveexec_b64 s[8:9], s[8:9]
	s_cbranch_execz .LBB0_1289
	s_mov_b64 s[8:9], exec
	s_waitcnt lgkmcnt(0)
	s_cmp_lg_u32 s98, 0
	s_cbranch_scc1 .Lfastbar_10
	buffer_wbl2 sc1
	s_waitcnt lgkmcnt(0)
	s_waitcnt vmcnt(0)
	v_mbcnt_lo_u32_b32 v1, s8, 0
	v_mbcnt_hi_u32_b32 v1, s9, v1
	v_cmp_eq_u32_e32 vcc, 0, v1
	s_and_saveexec_b64 s[10:11], vcc
	s_cbranch_execz .LBB0_1272
	s_bcnt1_i32_b64 s3, s[8:9]
	v_mov_b32_e32 v2, 0x7000
	v_mov_b32_e32 v3, s3
	global_atomic_add v2, v2, v3, s[34:35] offset:1024 sc0

.Llinv_10_1:
	s_and_saveexec_b64 s[10:11], vcc
	s_cbranch_execz .LBB0_1288
	s_bcnt1_i32_b64 s3, s[8:9]
	v_mov_b32_e32 v0, 0x2000
	v_mov_b32_e32 v1, s3
	global_atomic_add v0, v1, s[6:7] offset:1024
